# GEMM loops without per-block priority flips plus one static s_setprio 1 for waves 4-7 (set at the first GEMM prologue, kept)
# speedup vs baseline: 1.0105x; 1.0004x over previous
; #define PG8_STAGE(bufoff, gbase, voff) do { _Pragma("unroll") for (int _i = 0; _i < 2; ++_i) \
;         __builtin_amdgcn_global_load_lds((const unsigned*)((const char*)(gbase) + (voff)[_i]), (PG8_LAS unsigned*)(lds + (bufoff) + ldsw + _i * 8192), 16, 0, 0); } while (0)
; #define PG8_BAR __builtin_amdgcn_s_barrier()
; template <class Epi, class Sched, bool ALIGN_EPI = false, bool SP2 = false>
; __device__ __forceinline__ void gemm_phase(PG8_LAS unsigned char* lds, const Gemm g, const Sched& S, const Epi& E) {
;     ...
;     for (int i = 0; i < 2; ++i) { int R, C; stage_rc(tid * 16 + i * 8192, R, C); const int Rb = Epi::PERM ? ((R & ~31) + perm32(R & 31)) : R;
;         voffA[i] = (unsigned)(R * g.lda + C) * 2u; voffB[i] = (unsigned)(Rb * g.ldb + C) * 2u; }
;     const size_t kstep = (size_t)(BK * 2);
;     const size_t hstepA = (size_t)HALF * g.lda * 2, hstepB = (size_t)HALF * g.ldb * 2;
;     const size_t tstepA = 2 * hstepA, tstepB = 2 * hstepB;
;     const unsigned ldsw = (unsigned)wid * 1024u;
;     const int aoff = lds_byte(wr * 64 + fr, fq * 8), boff = lds_byte(wc * 32 + fr, fq * 8);
;     ...
;         PG8_STAGE(PG8_SB(0, 0), cB, voffB); PG8_STAGE(PG8_SB(0, 1), cB + hstepB, voffB); PG8_STAGE(PG8_SA(0, 0), cA, voffA); PG8_STAGE(PG8_SA(0, 1), cA + hstepA, voffA);
;         if (wr == 1) PG8_BAR;
.LBB0_137:
	s_or_b64 exec, exec, s[0:1]
	v_readlane_b32 s0, v252, 39
	v_mov_b32_e32 v3, v174
	v_readlane_b32 s1, v252, 40
	s_waitcnt lgkmcnt(0)
	s_barrier
	s_and_b64 vcc, exec, s[0:1]
	v_readfirstlane_b32 s4, v3
	s_cbranch_vccz .LBB0_153
	v_lshlrev_b32_e32 v0, 4, v3
	v_add_u32_e32 v4, 0x2000, v0
	v_ashrrev_i32_e32 v2, 31, v4
	v_lshrrev_b32_e32 v2, 22, v2
	v_add_u32_e32 v2, v4, v2
	v_ashrrev_i32_e32 v2, 10, v2
	v_mul_i32_i24_e32 v5, 0x400, v2
	v_sub_u32_e32 v4, v4, v5
	v_lshrrev_b32_e32 v5, 4, v4
	v_bitop3_b32 v5, v5, v4, 32 bitop3:0x6c
	v_ashrrev_i32_e32 v4, 31, v5
	v_lshrrev_b32_e32 v4, 26, v4
	v_add_u32_e32 v6, v5, v4
	v_lshlrev_b32_e32 v7, 3, v2
	v_ashrrev_i32_e32 v4, 6, v6
	v_and_b32_e32 v7, -16, v7
	v_add_u32_e32 v7, v4, v7
	v_and_b32_e32 v8, 3, v4
	s_mov_b32 s0, 0x1fffe0
	v_lshrrev_b32_e32 v9, 2, v7
	v_lshlrev_b32_e32 v10, 1, v7
	v_and_b32_e32 v6, 0xc0, v6
	v_and_or_b32 v8, v7, s0, v8
	v_and_b32_e32 v9, 4, v9
	v_and_b32_e32 v10, 24, v10
	v_sub_u32_e32 v5, v5, v6
	v_or3_b32 v8, v8, v9, v10
	v_lshlrev_b32_e32 v9, 5, v2
	v_ashrrev_i16_sdwa v5, v177, sext(v5) dst_sel:DWORD dst_unused:UNUSED_PAD src0_sel:DWORD src1_sel:BYTE_0
	v_and_b32_e32 v9, 32, v9
	v_bfe_i32 v5, v5, 0, 16
	v_add_lshl_u32 v6, v9, v5, 1
	v_lshl_add_u32 v150, v8, 11, v6
	v_lshl_add_u32 v152, v7, 11, v6
	v_bfe_i32 v6, v3, 27, 1
	v_lshrrev_b32_e32 v6, 22, v6
	v_add_u32_e32 v6, v0, v6
	v_and_b32_e32 v6, 0xfffffc00, v6
	v_sub_u32_e32 v0, v0, v6
	v_lshrrev_b32_e32 v6, 4, v0
	v_ashrrev_i32_e32 v7, 31, v3
	v_bitop3_b32 v0, v6, v0, 32 bitop3:0x6c
	v_lshrrev_b32_e32 v7, 26, v7
	v_ashrrev_i32_e32 v6, 31, v0
	v_add_u32_e32 v7, v3, v7
	v_lshrrev_b32_e32 v6, 26, v6
	v_ashrrev_i32_e32 v7, 6, v7
	v_add_u32_e32 v8, v0, v6
	v_lshlrev_b32_e32 v9, 3, v7
	v_ashrrev_i32_e32 v6, 6, v8
	v_and_b32_e32 v9, -16, v9
	v_add_u32_e32 v9, v6, v9
	v_and_b32_e32 v10, 3, v6
	v_lshrrev_b32_e32 v11, 2, v9
	v_lshlrev_b32_e32 v12, 1, v9
	v_and_b32_e32 v8, 0xc0, v8
	v_and_or_b32 v10, v9, s0, v10
	v_and_b32_e32 v11, 4, v11
	v_and_b32_e32 v12, 24, v12
	v_sub_u32_e32 v0, v0, v8
	s_ashr_i32 s10, s4, 6
	v_or3_b32 v10, v10, v11, v12
	v_lshlrev_b32_e32 v11, 5, v7
	v_ashrrev_i16_sdwa v0, v177, sext(v0) dst_sel:DWORD dst_unused:UNUSED_PAD src0_sel:DWORD src1_sel:BYTE_0
	s_lshl_b32 s8, s10, 10
	v_and_b32_e32 v11, 32, v11
	v_bfe_i32 v8, v0, 0, 16
	v_add_lshl_u32 v11, v11, v8, 1
	s_add_i32 s9, s8, 0
	v_readlane_b32 s0, v252, 52
	v_lshl_add_u32 v0, v10, 11, v11
	s_add_i32 m0, s9, 0x10000
	v_readlane_b32 s1, v252, 53
	v_lshl_add_u32 v154, v9, 11, v11
	s_add_i32 s30, s9, 0x2000
	s_add_i32 s31, s9, 0x4000
	s_add_i32 s34, s9, 0x6000
	s_ashr_i32 s11, s4, 8
	global_load_lds_dwordx4 v0, s[0:1]
	s_add_i32 m0, s9, 0x12000
	s_nop 0
	global_load_lds_dwordx4 v150, s[0:1]
	v_readlane_b32 s0, v252, 46
	s_add_i32 m0, s9, 0x14000
	v_readlane_b32 s1, v252, 47
	s_nop 4
	global_load_lds_dwordx4 v0, s[0:1]
	s_add_i32 m0, s9, 0x16000
	s_cmp_eq_u32 s11, 1
	global_load_lds_dwordx4 v150, s[0:1]
	v_readlane_b32 s0, v252, 48
	s_mov_b32 m0, s9
	v_readlane_b32 s1, v252, 49
	s_nop 4
	global_load_lds_dwordx4 v154, s[0:1]
	s_mov_b32 m0, s30
	s_nop 0
	global_load_lds_dwordx4 v152, s[0:1]
	v_readlane_b32 s0, v252, 50
	s_mov_b32 m0, s31
	v_readlane_b32 s1, v252, 51
	s_nop 4
	global_load_lds_dwordx4 v154, s[0:1]
	s_mov_b32 m0, s34
	s_nop 0
	global_load_lds_dwordx4 v152, s[0:1]
	s_cselect_b64 s[0:1], -1, 0
	s_cmp_lg_u32 s11, 1
	s_cbranch_scc1 .LBB0_140
	s_barrier
	s_setprio 1

; #define PG8_STAGE(bufoff, gbase, voff) do { _Pragma("unroll") for (int _i = 0; _i < 2; ++_i) \
;         __builtin_amdgcn_global_load_lds((const unsigned*)((const char*)(gbase) + (voff)[_i]), (PG8_LAS unsigned*)(lds + (bufoff) + ldsw + _i * 8192), 16, 0, 0); } while (0)
; #define PG8_BAR __builtin_amdgcn_s_barrier()
; template <class Epi, class Sched, bool ALIGN_EPI = false, bool SP2 = false>
; __device__ __forceinline__ void gemm_phase(PG8_LAS unsigned char* lds, const Gemm g, const Sched& S, const Epi& E) {
;     ...
;     for (int i = 0; i < 2; ++i) { int R, C; stage_rc(tid * 16 + i * 8192, R, C); const int Rb = Epi::PERM ? ((R & ~31) + perm32(R & 31)) : R;
;         voffA[i] = (unsigned)(R * g.lda + C) * 2u; voffB[i] = (unsigned)(Rb * g.ldb + C) * 2u; }
;     const size_t kstep = (size_t)(BK * 2);
;     const size_t hstepA = (size_t)HALF * g.lda * 2, hstepB = (size_t)HALF * g.ldb * 2;
;     const size_t tstepA = 2 * hstepA, tstepB = 2 * hstepB;
;     const unsigned ldsw = (unsigned)wid * 1024u;
;     const int aoff = lds_byte(wr * 64 + fr, fq * 8), boff = lds_byte(wc * 32 + fr, fq * 8);
;     ...
;         PG8_STAGE(PG8_SB(0, 0), cB, voffB); PG8_STAGE(PG8_SB(0, 1), cB + hstepB, voffB); PG8_STAGE(PG8_SA(0, 0), cA, voffA); PG8_STAGE(PG8_SA(0, 1), cA + hstepA, voffA);
;         if (wr == 1) PG8_BAR;
.LBB0_610:
	v_mov_b32_e32 v8, v174
	s_waitcnt vmcnt(0)
	s_barrier
	s_and_b64 vcc, exec, s[36:37]
	v_readfirstlane_b32 s4, v8
	s_cbranch_vccnz .LBB0_589
	v_lshlrev_b32_e32 v0, 4, v8
	v_add_u32_e32 v3, 0x2000, v0
	v_ashrrev_i32_e32 v2, 31, v3
	v_lshrrev_b32_e32 v2, 22, v2
	v_add_u32_e32 v2, v3, v2
	v_ashrrev_i32_e32 v2, 10, v2
	v_mul_i32_i24_e32 v4, 0x400, v2
	v_sub_u32_e32 v3, v3, v4
	v_lshrrev_b32_e32 v4, 4, v3
	v_bitop3_b32 v4, v4, v3, 32 bitop3:0x6c
	v_ashrrev_i32_e32 v3, 31, v4
	v_lshrrev_b32_e32 v3, 26, v3
	s_lshl_b64 s[8:9], s[88:89], 25
	v_readlane_b32 s10, v251, 31
	v_add_u32_e32 v5, v4, v3
	v_lshlrev_b32_e32 v6, 3, v2
	v_readlane_b32 s11, v251, 32
	s_add_u32 s30, s10, s8
	v_ashrrev_i32_e32 v3, 6, v5
	v_and_b32_e32 v6, -16, v6
	s_addc_u32 s31, s11, s9
	s_lshl_b64 s[8:9], s[88:89], 20
	v_readlane_b32 s10, v251, 39
	v_add_u32_e32 v6, v3, v6
	s_add_u32 s34, s10, s8
	v_and_b32_e32 v7, 3, v3
	s_mov_b32 s10, 0x3fffe0
	v_lshrrev_b32_e32 v9, 2, v6
	v_lshlrev_b32_e32 v10, 1, v6
	v_and_b32_e32 v5, 0xc0, v5
	v_and_or_b32 v7, v6, s10, v7
	v_and_b32_e32 v9, 4, v9
	v_and_b32_e32 v10, 24, v10
	v_sub_u32_e32 v4, v4, v5
	v_or3_b32 v7, v7, v9, v10
	v_lshlrev_b32_e32 v9, 5, v2
	v_ashrrev_i16_sdwa v4, v177, sext(v4) dst_sel:DWORD dst_unused:UNUSED_PAD src0_sel:DWORD src1_sel:BYTE_0
	v_and_b32_e32 v9, 32, v9
	v_bfe_i32 v4, v4, 0, 16
	v_add_lshl_u32 v5, v9, v4, 1
	v_lshl_add_u32 v150, v7, 10, v5
	v_lshl_add_u32 v152, v6, 10, v5
	v_bfe_i32 v5, v8, 27, 1
	v_lshrrev_b32_e32 v5, 22, v5
	v_add_u32_e32 v5, v0, v5
	v_and_b32_e32 v5, 0xfffffc00, v5
	v_sub_u32_e32 v0, v0, v5
	v_lshrrev_b32_e32 v5, 4, v0
	v_ashrrev_i32_e32 v6, 31, v8
	v_bitop3_b32 v0, v5, v0, 32 bitop3:0x6c
	v_lshrrev_b32_e32 v6, 26, v6
	v_ashrrev_i32_e32 v5, 31, v0
	v_add_u32_e32 v6, v8, v6
	v_lshrrev_b32_e32 v5, 26, v5
	v_ashrrev_i32_e32 v6, 6, v6
	v_add_u32_e32 v7, v0, v5
	v_lshlrev_b32_e32 v9, 3, v6
	v_ashrrev_i32_e32 v5, 6, v7
	v_and_b32_e32 v9, -16, v9
	v_add_u32_e32 v9, v5, v9
	v_readlane_b32 s8, v251, 40
	v_and_b32_e32 v10, 3, v5
	v_lshrrev_b32_e32 v11, 2, v9
	v_lshlrev_b32_e32 v12, 1, v9
	v_and_b32_e32 v7, 0xc0, v7
	s_addc_u32 s35, s8, s9
	s_ashr_i32 s8, s4, 6
	v_and_or_b32 v10, v9, s10, v10
	v_and_b32_e32 v11, 4, v11
	v_and_b32_e32 v12, 24, v12
	v_sub_u32_e32 v0, v0, v7
	s_ashr_i32 s53, s52, 31
	s_ashr_i32 s41, s40, 31
	s_ashr_i32 s9, s4, 8
	s_lshl_b32 s68, s8, 10
	v_or3_b32 v10, v10, v11, v12
	v_lshlrev_b32_e32 v11, 5, v6
	v_ashrrev_i16_sdwa v0, v177, sext(v0) dst_sel:DWORD dst_unused:UNUSED_PAD src0_sel:DWORD src1_sel:BYTE_0
	s_lshl_b64 s[10:11], s[52:53], 18
	s_lshl_b64 s[20:21], s[40:41], 18
	v_and_b32_e32 v11, 32, v11
	v_bfe_i32 v7, v0, 0, 16
	s_add_u32 s56, s34, s20
	v_add_lshl_u32 v11, v11, v7, 1
	s_addc_u32 s57, s35, s21
	s_add_i32 s53, s68, 0
	v_lshl_add_u32 v0, v10, 10, v11
	s_add_i32 m0, s53, 0x10000
	v_lshl_add_u32 v154, v9, 10, v11
	global_load_lds_dwordx4 v0, s[56:57]
	s_add_i32 m0, s53, 0x12000
	s_add_u32 s20, s56, 0x20000
	global_load_lds_dwordx4 v150, s[56:57]
	s_addc_u32 s21, s57, 0
	s_add_i32 m0, s53, 0x14000
	s_nop 0
	global_load_lds_dwordx4 v0, s[20:21]
	s_add_i32 m0, s53, 0x16000
	s_add_u32 s54, s30, s10
	s_addc_u32 s55, s31, s11
	s_add_i32 s69, s53, 0x2000
	global_load_lds_dwordx4 v150, s[20:21]
	s_mov_b32 m0, s53
	s_add_u32 s10, s54, 0x20000
	global_load_lds_dwordx4 v154, s[54:55]
	s_mov_b32 m0, s69
	s_addc_u32 s11, s55, 0
	s_add_i32 s94, s53, 0x4000
	global_load_lds_dwordx4 v152, s[54:55]
	s_mov_b32 m0, s94
	s_add_i32 s95, s53, 0x6000
	global_load_lds_dwordx4 v154, s[10:11]
	s_mov_b32 m0, s95
	s_cmp_eq_u32 s9, 1
	global_load_lds_dwordx4 v152, s[10:11]
	s_cselect_b64 s[20:21], -1, 0
	s_cmp_lg_u32 s9, 1
	s_cbranch_scc1 .LBB0_613
	s_barrier
	s_setprio 1

; #define PG8_STAGE(bufoff, gbase, voff) do { _Pragma("unroll") for (int _i = 0; _i < 2; ++_i) \
;         __builtin_amdgcn_global_load_lds((const unsigned*)((const char*)(gbase) + (voff)[_i]), (PG8_LAS unsigned*)(lds + (bufoff) + ldsw + _i * 8192), 16, 0, 0); } while (0)
; #define PG8_BAR __builtin_amdgcn_s_barrier()
; template <class Epi, class Sched, bool ALIGN_EPI = false, bool SP2 = false>
; __device__ __forceinline__ void gemm_phase(PG8_LAS unsigned char* lds, const Gemm g, const Sched& S, const Epi& E) {
;     ...
;     for (int i = 0; i < 2; ++i) { int R, C; stage_rc(tid * 16 + i * 8192, R, C); const int Rb = Epi::PERM ? ((R & ~31) + perm32(R & 31)) : R;
;         voffA[i] = (unsigned)(R * g.lda + C) * 2u; voffB[i] = (unsigned)(Rb * g.ldb + C) * 2u; }
;     const size_t kstep = (size_t)(BK * 2);
;     const size_t hstepA = (size_t)HALF * g.lda * 2, hstepB = (size_t)HALF * g.ldb * 2;
;     const size_t tstepA = 2 * hstepA, tstepB = 2 * hstepB;
;     const unsigned ldsw = (unsigned)wid * 1024u;
;     const int aoff = lds_byte(wr * 64 + fr, fq * 8), boff = lds_byte(wc * 32 + fr, fq * 8);
;     ...
;         PG8_STAGE(PG8_SB(0, 0), cB, voffB); PG8_STAGE(PG8_SB(0, 1), cB + hstepB, voffB); PG8_STAGE(PG8_SA(0, 0), cA, voffA); PG8_STAGE(PG8_SA(0, 1), cA + hstepA, voffA);
;         if (wr == 1) PG8_BAR;
.LBB0_713:
	s_or_b64 exec, exec, s[0:1]
	v_mov_b32_e32 v3, v174
	s_waitcnt lgkmcnt(0)
	s_barrier
	s_and_b64 vcc, exec, s[36:37]
	v_readfirstlane_b32 s4, v3
	s_cbranch_vccnz .LBB0_733
	v_lshlrev_b32_e32 v0, 4, v3
	v_add_u32_e32 v4, 0x2000, v0
	v_ashrrev_i32_e32 v2, 31, v4
	v_lshrrev_b32_e32 v2, 22, v2
	v_add_u32_e32 v2, v4, v2
	v_ashrrev_i32_e32 v2, 10, v2
	v_mul_i32_i24_e32 v5, 0x400, v2
	v_sub_u32_e32 v4, v4, v5
	v_lshrrev_b32_e32 v5, 4, v4
	v_bitop3_b32 v5, v5, v4, 32 bitop3:0x6c
	v_ashrrev_i32_e32 v4, 31, v5
	v_lshrrev_b32_e32 v4, 26, v4
	v_add_u32_e32 v6, v5, v4
	v_lshlrev_b32_e32 v7, 3, v2
	v_ashrrev_i32_e32 v4, 6, v6
	v_and_b32_e32 v7, -16, v7
	v_add_u32_e32 v7, v4, v7
	v_and_b32_e32 v8, 3, v4
	s_mov_b32 s0, 0x1fffe0
	v_lshrrev_b32_e32 v9, 2, v7
	v_lshlrev_b32_e32 v10, 1, v7
	v_and_b32_e32 v6, 0xc0, v6
	v_and_or_b32 v8, v7, s0, v8
	v_and_b32_e32 v9, 4, v9
	v_and_b32_e32 v10, 24, v10
	v_sub_u32_e32 v5, v5, v6
	v_or3_b32 v8, v8, v9, v10
	v_lshlrev_b32_e32 v9, 5, v2
	v_ashrrev_i16_sdwa v5, v177, sext(v5) dst_sel:DWORD dst_unused:UNUSED_PAD src0_sel:DWORD src1_sel:BYTE_0
	v_and_b32_e32 v9, 32, v9
	v_bfe_i32 v5, v5, 0, 16
	v_add_lshl_u32 v6, v9, v5, 1
	v_lshl_add_u32 v150, v8, 11, v6
	v_lshl_add_u32 v152, v7, 11, v6
	v_bfe_i32 v6, v3, 27, 1
	v_lshrrev_b32_e32 v6, 22, v6
	v_add_u32_e32 v6, v0, v6
	v_and_b32_e32 v6, 0xfffffc00, v6
	v_sub_u32_e32 v0, v0, v6
	v_lshrrev_b32_e32 v6, 4, v0
	v_ashrrev_i32_e32 v7, 31, v3
	v_bitop3_b32 v0, v6, v0, 32 bitop3:0x6c
	v_lshrrev_b32_e32 v7, 26, v7
	v_ashrrev_i32_e32 v6, 31, v0
	v_add_u32_e32 v7, v3, v7
	v_lshrrev_b32_e32 v6, 26, v6
	v_ashrrev_i32_e32 v7, 6, v7
	v_add_u32_e32 v8, v0, v6
	v_lshlrev_b32_e32 v9, 3, v7
	v_ashrrev_i32_e32 v6, 6, v8
	v_and_b32_e32 v9, -16, v9
	v_add_u32_e32 v9, v6, v9
	v_and_b32_e32 v10, 3, v6
	v_lshrrev_b32_e32 v11, 2, v9
	v_lshlrev_b32_e32 v12, 1, v9
	v_and_b32_e32 v8, 0xc0, v8
	v_and_or_b32 v10, v9, s0, v10
	v_and_b32_e32 v11, 4, v11
	v_and_b32_e32 v12, 24, v12
	v_sub_u32_e32 v0, v0, v8
	s_ashr_i32 s10, s4, 6
	v_or3_b32 v10, v10, v11, v12
	v_lshlrev_b32_e32 v11, 5, v7
	v_ashrrev_i16_sdwa v0, v177, sext(v0) dst_sel:DWORD dst_unused:UNUSED_PAD src0_sel:DWORD src1_sel:BYTE_0
	s_lshl_b32 s8, s10, 10
	v_and_b32_e32 v11, 32, v11
	v_bfe_i32 v8, v0, 0, 16
	v_add_lshl_u32 v11, v11, v8, 1
	s_add_i32 s9, s8, 0
	v_readlane_b32 s0, v254, 2
	v_lshl_add_u32 v0, v10, 11, v11
	s_add_i32 m0, s9, 0x10000
	v_readlane_b32 s1, v254, 3
	v_lshl_add_u32 v154, v9, 11, v11
	s_add_i32 s30, s9, 0x2000
	s_add_i32 s31, s9, 0x4000
	s_add_i32 s34, s9, 0x6000
	s_ashr_i32 s11, s4, 8
	global_load_lds_dwordx4 v0, s[0:1]
	s_add_i32 m0, s9, 0x12000
	s_nop 0
	global_load_lds_dwordx4 v150, s[0:1]
	v_readlane_b32 s0, v253, 60
	s_add_i32 m0, s9, 0x14000
	v_readlane_b32 s1, v253, 61
	s_nop 4
	global_load_lds_dwordx4 v0, s[0:1]
	s_add_i32 m0, s9, 0x16000
	s_cmp_eq_u32 s11, 1
	global_load_lds_dwordx4 v150, s[0:1]
	v_readlane_b32 s0, v253, 62
	s_mov_b32 m0, s9
	v_readlane_b32 s1, v253, 63
	s_nop 4
	global_load_lds_dwordx4 v154, s[0:1]
	s_mov_b32 m0, s30
	s_nop 0
	global_load_lds_dwordx4 v152, s[0:1]
	v_readlane_b32 s0, v254, 0
	s_mov_b32 m0, s31
	v_readlane_b32 s1, v254, 1
	s_nop 4
	global_load_lds_dwordx4 v154, s[0:1]
	s_mov_b32 m0, s34
	s_nop 0
	global_load_lds_dwordx4 v152, s[0:1]
	s_cselect_b64 s[0:1], -1, 0
	s_cmp_lg_u32 s11, 1
	s_cbranch_scc1 .LBB0_716
	s_barrier
	s_setprio 1

; #define PG8_STAGE(bufoff, gbase, voff) do { _Pragma("unroll") for (int _i = 0; _i < 2; ++_i) \
;         __builtin_amdgcn_global_load_lds((const unsigned*)((const char*)(gbase) + (voff)[_i]), (PG8_LAS unsigned*)(lds + (bufoff) + ldsw + _i * 8192), 16, 0, 0); } while (0)
; #define PG8_BAR __builtin_amdgcn_s_barrier()
; template <class Epi, class Sched, bool ALIGN_EPI = false, bool SP2 = false>
; __device__ __forceinline__ void gemm_phase(PG8_LAS unsigned char* lds, const Gemm g, const Sched& S, const Epi& E) {
;     ...
;     for (int i = 0; i < 2; ++i) { int R, C; stage_rc(tid * 16 + i * 8192, R, C); const int Rb = Epi::PERM ? ((R & ~31) + perm32(R & 31)) : R;
;         voffA[i] = (unsigned)(R * g.lda + C) * 2u; voffB[i] = (unsigned)(Rb * g.ldb + C) * 2u; }
;     const size_t kstep = (size_t)(BK * 2);
;     const size_t hstepA = (size_t)HALF * g.lda * 2, hstepB = (size_t)HALF * g.ldb * 2;
;     const size_t tstepA = 2 * hstepA, tstepB = 2 * hstepB;
;     const unsigned ldsw = (unsigned)wid * 1024u;
;     const int aoff = lds_byte(wr * 64 + fr, fq * 8), boff = lds_byte(wc * 32 + fr, fq * 8);
;     ...
;         PG8_STAGE(PG8_SB(0, 0), cB, voffB); PG8_STAGE(PG8_SB(0, 1), cB + hstepB, voffB); PG8_STAGE(PG8_SA(0, 0), cA, voffA); PG8_STAGE(PG8_SA(0, 1), cA + hstepA, voffA);
;         if (wr == 1) PG8_BAR;
.LBB0_843:
	s_or_b64 exec, exec, s[0:1]
	v_readlane_b32 s0, v254, 6
	v_mov_b32_e32 v3, v174
	v_readlane_b32 s1, v254, 7
	s_waitcnt lgkmcnt(0)
	s_barrier
	s_and_b64 vcc, exec, s[0:1]
	v_readfirstlane_b32 s4, v3
	s_cbranch_vccz .LBB0_863
	v_lshlrev_b32_e32 v0, 4, v3
	v_add_u32_e32 v4, 0x2000, v0
	v_ashrrev_i32_e32 v2, 31, v4
	v_lshrrev_b32_e32 v2, 22, v2
	v_add_u32_e32 v2, v4, v2
	v_ashrrev_i32_e32 v2, 10, v2
	v_mul_i32_i24_e32 v5, 0x400, v2
	v_sub_u32_e32 v4, v4, v5
	v_lshrrev_b32_e32 v5, 4, v4
	v_bitop3_b32 v5, v5, v4, 32 bitop3:0x6c
	v_ashrrev_i32_e32 v4, 31, v5
	v_lshrrev_b32_e32 v4, 26, v4
	v_add_u32_e32 v6, v5, v4
	v_lshlrev_b32_e32 v7, 3, v2
	v_ashrrev_i32_e32 v4, 6, v6
	v_and_b32_e32 v7, -16, v7
	v_add_u32_e32 v7, v4, v7
	v_and_b32_e32 v8, 3, v4
	s_mov_b32 s0, 0x1fffe0
	v_lshrrev_b32_e32 v9, 2, v7
	v_lshlrev_b32_e32 v10, 1, v7
	v_and_b32_e32 v6, 0xc0, v6
	v_and_or_b32 v8, v7, s0, v8
	v_and_b32_e32 v9, 4, v9
	v_and_b32_e32 v10, 24, v10
	v_sub_u32_e32 v5, v5, v6
	v_or3_b32 v8, v8, v9, v10
	v_lshlrev_b32_e32 v9, 5, v2
	v_ashrrev_i16_sdwa v5, v177, sext(v5) dst_sel:DWORD dst_unused:UNUSED_PAD src0_sel:DWORD src1_sel:BYTE_0
	v_and_b32_e32 v9, 32, v9
	v_bfe_i32 v5, v5, 0, 16
	v_add_lshl_u32 v6, v9, v5, 1
	v_lshl_add_u32 v150, v8, 11, v6
	v_lshl_add_u32 v152, v7, 11, v6
	v_bfe_i32 v6, v3, 27, 1
	v_lshrrev_b32_e32 v6, 22, v6
	v_add_u32_e32 v6, v0, v6
	v_and_b32_e32 v6, 0xfffffc00, v6
	v_sub_u32_e32 v0, v0, v6
	v_lshrrev_b32_e32 v6, 4, v0
	v_ashrrev_i32_e32 v7, 31, v3
	v_bitop3_b32 v0, v6, v0, 32 bitop3:0x6c
	v_lshrrev_b32_e32 v7, 26, v7
	v_ashrrev_i32_e32 v6, 31, v0
	v_add_u32_e32 v7, v3, v7
	v_lshrrev_b32_e32 v6, 26, v6
	v_ashrrev_i32_e32 v7, 6, v7
	v_add_u32_e32 v8, v0, v6
	v_lshlrev_b32_e32 v9, 3, v7
	v_ashrrev_i32_e32 v6, 6, v8
	v_and_b32_e32 v9, -16, v9
	v_add_u32_e32 v9, v6, v9
	v_and_b32_e32 v10, 3, v6
	v_lshrrev_b32_e32 v11, 2, v9
	v_lshlrev_b32_e32 v12, 1, v9
	v_and_b32_e32 v8, 0xc0, v8
	v_and_or_b32 v10, v9, s0, v10
	v_and_b32_e32 v11, 4, v11
	v_and_b32_e32 v12, 24, v12
	v_sub_u32_e32 v0, v0, v8
	s_ashr_i32 s10, s4, 6
	v_or3_b32 v10, v10, v11, v12
	v_lshlrev_b32_e32 v11, 5, v7
	v_ashrrev_i16_sdwa v0, v177, sext(v0) dst_sel:DWORD dst_unused:UNUSED_PAD src0_sel:DWORD src1_sel:BYTE_0
	s_lshl_b32 s8, s10, 10
	v_and_b32_e32 v11, 32, v11
	v_bfe_i32 v8, v0, 0, 16
	v_add_lshl_u32 v11, v11, v8, 1
	s_add_i32 s9, s8, 0
	v_readlane_b32 s0, v254, 19
	v_lshl_add_u32 v0, v10, 11, v11
	s_add_i32 m0, s9, 0x10000
	v_readlane_b32 s1, v254, 20
	v_lshl_add_u32 v154, v9, 11, v11
	s_add_i32 s30, s9, 0x2000
	s_add_i32 s31, s9, 0x4000
	s_add_i32 s34, s9, 0x6000
	s_ashr_i32 s11, s4, 8
	global_load_lds_dwordx4 v0, s[0:1]
	s_add_i32 m0, s9, 0x12000
	s_nop 0
	global_load_lds_dwordx4 v150, s[0:1]
	v_readlane_b32 s0, v254, 13
	s_add_i32 m0, s9, 0x14000
	v_readlane_b32 s1, v254, 14
	s_nop 4
	global_load_lds_dwordx4 v0, s[0:1]
	s_add_i32 m0, s9, 0x16000
	s_cmp_eq_u32 s11, 1
	global_load_lds_dwordx4 v150, s[0:1]
	v_readlane_b32 s0, v254, 15
	s_mov_b32 m0, s9
	v_readlane_b32 s1, v254, 16
	s_nop 4
	global_load_lds_dwordx4 v154, s[0:1]
	s_mov_b32 m0, s30
	s_nop 0
	global_load_lds_dwordx4 v152, s[0:1]
	v_readlane_b32 s0, v254, 17
	s_mov_b32 m0, s31
	v_readlane_b32 s1, v254, 18
	s_nop 4
	global_load_lds_dwordx4 v154, s[0:1]
	s_mov_b32 m0, s34
	s_nop 0
	global_load_lds_dwordx4 v152, s[0:1]
	s_cselect_b64 s[0:1], -1, 0
	s_cmp_lg_u32 s11, 1
	s_cbranch_scc1 .LBB0_846
	s_barrier
	s_setprio 1

; #define PG8_STAGE(bufoff, gbase, voff) do { _Pragma("unroll") for (int _i = 0; _i < 2; ++_i) \
;         __builtin_amdgcn_global_load_lds((const unsigned*)((const char*)(gbase) + (voff)[_i]), (PG8_LAS unsigned*)(lds + (bufoff) + ldsw + _i * 8192), 16, 0, 0); } while (0)
; #define PG8_BAR __builtin_amdgcn_s_barrier()
; template <class Epi, class Sched, bool ALIGN_EPI = false, bool SP2 = false>
; __device__ __forceinline__ void gemm_phase(PG8_LAS unsigned char* lds, const Gemm g, const Sched& S, const Epi& E) {
;     ...
;     for (int i = 0; i < 2; ++i) { int R, C; stage_rc(tid * 16 + i * 8192, R, C); const int Rb = Epi::PERM ? ((R & ~31) + perm32(R & 31)) : R;
;         voffA[i] = (unsigned)(R * g.lda + C) * 2u; voffB[i] = (unsigned)(Rb * g.ldb + C) * 2u; }
;     const size_t kstep = (size_t)(BK * 2);
;     const size_t hstepA = (size_t)HALF * g.lda * 2, hstepB = (size_t)HALF * g.ldb * 2;
;     const size_t tstepA = 2 * hstepA, tstepB = 2 * hstepB;
;     const unsigned ldsw = (unsigned)wid * 1024u;
;     const int aoff = lds_byte(wr * 64 + fr, fq * 8), boff = lds_byte(wc * 32 + fr, fq * 8);
;     ...
;         PG8_STAGE(PG8_SB(0, 0), cB, voffB); PG8_STAGE(PG8_SB(0, 1), cB + hstepB, voffB); PG8_STAGE(PG8_SA(0, 0), cA, voffA); PG8_STAGE(PG8_SA(0, 1), cA + hstepA, voffA);
;         if (wr == 1) PG8_BAR;
.LBB0_916:
	s_or_b64 exec, exec, s[0:1]
	v_mov_b32_e32 v3, v174
	s_waitcnt lgkmcnt(0)
	s_barrier
	s_and_b64 vcc, exec, s[36:37]
	v_readfirstlane_b32 s4, v3
	s_cbranch_vccnz .LBB0_936
	v_lshlrev_b32_e32 v0, 4, v3
	v_add_u32_e32 v4, 0x2000, v0
	v_ashrrev_i32_e32 v2, 31, v4
	v_lshrrev_b32_e32 v2, 22, v2
	v_add_u32_e32 v2, v4, v2
	v_ashrrev_i32_e32 v2, 10, v2
	v_mul_i32_i24_e32 v5, 0x400, v2
	v_sub_u32_e32 v4, v4, v5
	v_lshrrev_b32_e32 v5, 4, v4
	v_bitop3_b32 v5, v5, v4, 32 bitop3:0x6c
	v_ashrrev_i32_e32 v4, 31, v5
	v_lshrrev_b32_e32 v4, 26, v4
	v_add_u32_e32 v6, v5, v4
	v_lshlrev_b32_e32 v7, 3, v2
	v_ashrrev_i32_e32 v4, 6, v6
	v_and_b32_e32 v7, -16, v7
	v_add_u32_e32 v7, v4, v7
	v_and_b32_e32 v8, 3, v4
	s_mov_b32 s0, 0x7ffe0
	v_lshrrev_b32_e32 v9, 2, v7
	v_lshlrev_b32_e32 v10, 1, v7
	v_and_b32_e32 v6, 0xc0, v6
	v_and_or_b32 v8, v7, s0, v8
	v_and_b32_e32 v9, 4, v9
	v_and_b32_e32 v10, 24, v10
	v_sub_u32_e32 v5, v5, v6
	v_or3_b32 v8, v8, v9, v10
	v_lshlrev_b32_e32 v9, 5, v2
	v_ashrrev_i16_sdwa v5, v177, sext(v5) dst_sel:DWORD dst_unused:UNUSED_PAD src0_sel:DWORD src1_sel:BYTE_0
	v_and_b32_e32 v9, 32, v9
	v_bfe_i32 v5, v5, 0, 16
	v_add_lshl_u32 v6, v9, v5, 1
	v_lshl_add_u32 v150, v8, 13, v6
	v_lshl_add_u32 v152, v7, 13, v6
	v_bfe_i32 v6, v3, 27, 1
	v_lshrrev_b32_e32 v6, 22, v6
	v_add_u32_e32 v6, v0, v6
	v_and_b32_e32 v6, 0xfffffc00, v6
	v_sub_u32_e32 v0, v0, v6
	v_lshrrev_b32_e32 v6, 4, v0
	v_ashrrev_i32_e32 v7, 31, v3
	v_bitop3_b32 v0, v6, v0, 32 bitop3:0x6c
	v_lshrrev_b32_e32 v7, 26, v7
	v_ashrrev_i32_e32 v6, 31, v0
	v_add_u32_e32 v7, v3, v7
	v_lshrrev_b32_e32 v6, 26, v6
	v_ashrrev_i32_e32 v7, 6, v7
	v_add_u32_e32 v8, v0, v6
	v_lshlrev_b32_e32 v9, 3, v7
	v_ashrrev_i32_e32 v6, 6, v8
	v_and_b32_e32 v9, -16, v9
	v_add_u32_e32 v9, v6, v9
	v_and_b32_e32 v10, 3, v6
	v_lshrrev_b32_e32 v11, 2, v9
	v_lshlrev_b32_e32 v12, 1, v9
	v_and_b32_e32 v8, 0xc0, v8
	v_and_or_b32 v10, v9, s0, v10
	v_and_b32_e32 v11, 4, v11
	v_and_b32_e32 v12, 24, v12
	v_sub_u32_e32 v0, v0, v8
	s_ashr_i32 s10, s4, 6
	v_or3_b32 v10, v10, v11, v12
	v_lshlrev_b32_e32 v11, 5, v7
	v_ashrrev_i16_sdwa v0, v177, sext(v0) dst_sel:DWORD dst_unused:UNUSED_PAD src0_sel:DWORD src1_sel:BYTE_0
	s_lshl_b32 s8, s10, 10
	v_and_b32_e32 v11, 32, v11
	v_bfe_i32 v8, v0, 0, 16
	v_add_lshl_u32 v11, v11, v8, 1
	s_add_i32 s9, s8, 0
	v_readlane_b32 s0, v254, 36
	v_lshl_add_u32 v0, v10, 13, v11
	s_add_i32 m0, s9, 0x10000
	v_readlane_b32 s1, v254, 37
	v_lshl_add_u32 v154, v9, 13, v11
	s_add_i32 s30, s9, 0x2000
	s_add_i32 s31, s9, 0x4000
	s_add_i32 s34, s9, 0x6000
	s_ashr_i32 s11, s4, 8
	global_load_lds_dwordx4 v0, s[0:1]
	s_add_i32 m0, s9, 0x12000
	s_nop 0
	global_load_lds_dwordx4 v150, s[0:1]
	v_readlane_b32 s0, v254, 27
	s_add_i32 m0, s9, 0x14000
	v_readlane_b32 s1, v254, 28
	s_nop 4
	global_load_lds_dwordx4 v0, s[0:1]
	s_add_i32 m0, s9, 0x16000
	s_cmp_eq_u32 s11, 1
	global_load_lds_dwordx4 v150, s[0:1]
	v_readlane_b32 s0, v254, 32
	s_mov_b32 m0, s9
	v_readlane_b32 s1, v254, 33
	s_nop 4
	global_load_lds_dwordx4 v154, s[0:1]
	s_mov_b32 m0, s30
	s_nop 0
	global_load_lds_dwordx4 v152, s[0:1]
	v_readlane_b32 s0, v254, 34
	s_mov_b32 m0, s31
	v_readlane_b32 s1, v254, 35
	s_nop 4
	global_load_lds_dwordx4 v154, s[0:1]
	s_mov_b32 m0, s34
	s_nop 0
	global_load_lds_dwordx4 v152, s[0:1]
	s_cselect_b64 s[0:1], -1, 0
	s_cmp_lg_u32 s11, 1
	s_cbranch_scc1 .LBB0_919
	s_barrier
	s_setprio 1
